# attention B: running-max shift carried in the QK accumulator init (refreshed on lazy rescale), 32 per-tile subtractions removed; bias fragments in two halves
# speedup vs baseline: 1.0042x; 1.0004x over previous
.LBB0_386:
	v_mov_b32_e32 v15, 0
	s_cmp_gt_i32 s35, s12
	v_mov_b32_e32 v14, v15
	v_mov_b32_e32 v13, v15
	v_mov_b32_e32 v12, v15
	v_mov_b32_e32 v11, v15
	v_mov_b32_e32 v10, v15
	v_mov_b32_e32 v9, v15
	v_mov_b32_e32 v8, v15
	v_mov_b32_e32 v7, v15
	v_mov_b32_e32 v6, v15
	v_mov_b32_e32 v5, v15
	v_mov_b32_e32 v4, v15
	v_mov_b32_e32 v3, v15
	v_mov_b32_e32 v2, v15
	v_mov_b32_e32 v1, v15
	v_mov_b32_e32 v0, v15
	v_mov_b32_e32 v31, v15
	v_mov_b32_e32 v30, v15
	v_mov_b32_e32 v29, v15
	v_mov_b32_e32 v28, v15
	v_mov_b32_e32 v27, v15
	v_mov_b32_e32 v26, v15
	v_mov_b32_e32 v25, v15
	v_mov_b32_e32 v24, v15
	v_mov_b32_e32 v23, v15
	v_mov_b32_e32 v22, v15
	v_mov_b32_e32 v21, v15
	v_mov_b32_e32 v20, v15
	v_mov_b32_e32 v19, v15
	v_mov_b32_e32 v18, v15
	v_mov_b32_e32 v17, v15
	v_mov_b32_e32 v16, v15
	v_mov_b32_e32 v101, v15
	s_cbranch_scc1 .LBB0_379
	v_or_b32_e32 v0, s37, v178
	s_add_i32 s35, s12, s41
	s_bfe_u32 s38, s16, 0x4000b
	v_sub_u32_e32 v0, v108, v0
	s_max_i32 s36, s35, 8
	s_mul_i32 s43, s38, 0xc00000
	s_and_b32 s38, s27, 7
	v_and_b32_e32 v0, 3, v0
	v_mov_b32_e32 v1, s26
	s_lshl_b32 s37, s42, 14
	s_add_i32 s36, s36, -8
	s_lshl_b32 s44, s38, 7
	v_mad_u32_u24 v117, v0, s25, v1
	s_add_i32 s37, s37, 0xfffe0000
	v_lshl_add_u32 v0, s42, 8, v112
	s_lshl_b32 s13, s13, 10
	s_add_i32 s38, s42, -5
	s_mul_i32 s45, s42, 0x60000
	v_subrev_u32_e32 v118, s13, v0
	s_mul_hi_u32 s13, s42, 0x60000
	s_add_u32 s43, s43, s45
	s_addc_u32 s13, 0, s13
	s_or_b32 s43, s43, s44
	s_mulk_i32 s39, 0x6000
	v_add_u32_e32 v0, s39, v113
	s_add_u32 s44, s14, s43
	v_add_u32_e32 v98, v0, v32
	s_addc_u32 s45, s15, s13
	v_lshl_add_u64 v[102:103], v[98:99], 1, s[44:45]
	s_add_u32 s44, s19, s43
	v_add_u32_e32 v98, v0, v115
	s_addc_u32 s45, s20, s13
	s_sub_i32 s39, 0, s12
	s_sub_i32 s12, s12, s42
	v_mov_b32_e32 v101, 0
	v_lshl_add_u64 v[104:105], v[98:99], 1, s[44:45]
	s_add_i32 s42, s12, 11
	v_mov_b32_e32 v119, 0xf149f2ca
	v_mov_b32_e32 v136, 0
	v_mov_b32_e32 v137, 0
	v_mov_b32_e32 v138, 0
	v_mov_b32_e32 v139, 0
	v_mov_b32_e32 v140, 0
	v_mov_b32_e32 v141, 0
	v_mov_b32_e32 v142, 0
	v_mov_b32_e32 v143, 0
	v_mov_b32_e32 v144, 0
	v_mov_b32_e32 v145, 0
	v_mov_b32_e32 v146, 0
	v_mov_b32_e32 v147, 0
	v_mov_b32_e32 v148, 0
	v_mov_b32_e32 v149, 0
	v_mov_b32_e32 v150, 0
	v_mov_b32_e32 v151, 0
	v_mov_b32_e32 v164, 0
	v_mov_b32_e32 v165, 0xf149f2ca
	v_mov_b32_e32 v16, 0
	v_mov_b32_e32 v17, v101
	v_mov_b32_e32 v18, v101
	v_mov_b32_e32 v19, v101
	v_mov_b32_e32 v20, v101
	v_mov_b32_e32 v21, v101
	v_mov_b32_e32 v22, v101
	v_mov_b32_e32 v23, v101
	v_mov_b32_e32 v24, v101
	v_mov_b32_e32 v25, v101
	v_mov_b32_e32 v26, v101
	v_mov_b32_e32 v27, v101
	v_mov_b32_e32 v28, v101
	v_mov_b32_e32 v29, v101
	v_mov_b32_e32 v30, v101
	v_mov_b32_e32 v31, v101
	v_mov_b32_e32 v0, v101
	v_mov_b32_e32 v1, v101
	v_mov_b32_e32 v2, v101
	v_mov_b32_e32 v3, v101
	v_mov_b32_e32 v4, v101
	v_mov_b32_e32 v5, v101
	v_mov_b32_e32 v6, v101
	v_mov_b32_e32 v7, v101
	v_mov_b32_e32 v8, v101
	v_mov_b32_e32 v9, v101
	v_mov_b32_e32 v10, v101
	v_mov_b32_e32 v11, v101
	v_mov_b32_e32 v12, v101
	v_mov_b32_e32 v13, v101
	v_mov_b32_e32 v14, v101
	v_mov_b32_e32 v15, v101
	s_cmp_lt_i32 s42, 2
	s_mov_b64 s[12:13], -1
	s_cbranch_scc0 .LBB0_393

.LBB0_397:
	s_add_i32 s43, s38, -3
	s_cmp_lt_u32 s43, s36
	s_cselect_b64 s[12:13], -1, 0
	s_cmp_gt_i32 s43, s35
	s_cselect_b64 s[44:45], -1, 0
	s_or_b64 s[12:13], s[12:13], s[44:45]
	s_and_b64 vcc, exec, s[12:13]
	s_cbranch_vccnz .LBB0_401
	s_and_b32 s12, s37, 0xc000
	s_add_i32 s12, s12, 0
	v_add_u32_e32 v125, s12, v174
	v_add_u32_e32 v126, v125, v173
	v_add_u32_e32 v127, v125, v177
	v_add_u32_e32 v128, v125, v179
	v_add_u32_e32 v129, v125, v180
	ds_read_b128 v[152:155], v126
	ds_read_b128 v[156:159], v126 offset:4096
	ds_read_b128 v[160:163], v127
	ds_read_b128 v[184:187], v127 offset:4096
	ds_read_b128 v[188:191], v128
	ds_read_b128 v[192:195], v128 offset:4096
	ds_read_b128 v[244:247], v129
	ds_read_b128 v[248:251], v129 offset:4096
	v_and_b32_e32 v131, -16, v118
	v_add_u32_e32 v131, v117, v131
	s_waitcnt lgkmcnt(6)
	v_mfma_f32_32x32x16_bf16 v[32:47], v[152:155], v[64:67], v[136:151]
	v_mfma_f32_32x32x16_bf16 v[48:63], v[156:159], v[64:67], v[136:151]
	ds_read_b128 v[200:203], v131
	ds_read_b128 v[204:207], v131 offset:32
	ds_read_b128 v[208:211], v131 offset:64
	ds_read_b128 v[252:255], v131 offset:96
	s_waitcnt lgkmcnt(8)
	v_mfma_f32_32x32x16_bf16 v[32:47], v[160:163], v[68:71], v[32:47]
	v_mfma_f32_32x32x16_bf16 v[48:63], v[184:187], v[68:71], v[48:63]
	s_waitcnt lgkmcnt(6)
	v_mfma_f32_32x32x16_bf16 v[32:47], v[188:191], v[72:75], v[32:47]
	v_mfma_f32_32x32x16_bf16 v[48:63], v[192:195], v[72:75], v[48:63]
	s_waitcnt lgkmcnt(4)
	v_mfma_f32_32x32x16_bf16 v[32:47], v[244:247], v[76:79], v[32:47]
	v_mfma_f32_32x32x16_bf16 v[48:63], v[248:251], v[76:79], v[48:63]
	v_add_u32_e32 v129, s12, v106
	v_add3_u32 v129, v129, v175, v176
	v_add_u32_e32 v130, v129, v109
	v_add_u32_e32 v129, v129, v107
	s_waitcnt lgkmcnt(0)
	ds_read_b64_tr_b16 v[152:153], v129 offset:8192
	ds_read_b64_tr_b16 v[154:155], v129 offset:9216
	ds_read_b64_tr_b16 v[156:157], v130 offset:8192
	ds_read_b64_tr_b16 v[158:159], v130 offset:9216
	ds_read_b64_tr_b16 v[160:161], v129 offset:10240
	ds_read_b64_tr_b16 v[162:163], v129 offset:11264
	ds_read_b64_tr_b16 v[184:185], v130 offset:10240
	ds_read_b64_tr_b16 v[186:187], v130 offset:11264
	ds_read_b64_tr_b16 v[188:189], v129 offset:12288
	ds_read_b64_tr_b16 v[190:191], v129 offset:13312
	ds_read_b64_tr_b16 v[192:193], v130 offset:12288
	v_fmamk_f32 v32, v32, 0x3e38aa3b, v200
	v_fmamk_f32 v33, v33, 0x3e38aa3b, v201
	v_fmamk_f32 v34, v34, 0x3e38aa3b, v202
	v_fmamk_f32 v35, v35, 0x3e38aa3b, v203
	v_fmamk_f32 v36, v36, 0x3e38aa3b, v204
	v_fmamk_f32 v37, v37, 0x3e38aa3b, v205
	v_fmamk_f32 v38, v38, 0x3e38aa3b, v206
	v_fmamk_f32 v39, v39, 0x3e38aa3b, v207
	v_fmamk_f32 v40, v40, 0x3e38aa3b, v208
	v_fmamk_f32 v41, v41, 0x3e38aa3b, v209
	v_fmamk_f32 v42, v42, 0x3e38aa3b, v210
	v_fmamk_f32 v43, v43, 0x3e38aa3b, v211
	v_fmamk_f32 v44, v44, 0x3e38aa3b, v252
	v_fmamk_f32 v45, v45, 0x3e38aa3b, v253
	v_fmamk_f32 v46, v46, 0x3e38aa3b, v254
	v_fmamk_f32 v47, v47, 0x3e38aa3b, v255
	ds_read_b128 v[200:203], v131 offset:128
	ds_read_b128 v[204:207], v131 offset:160
	ds_read_b128 v[208:211], v131 offset:192
	ds_read_b128 v[252:255], v131 offset:224
	s_waitcnt lgkmcnt(0)
	ds_read_b64_tr_b16 v[194:195], v130 offset:13312
	ds_read_b64_tr_b16 v[244:245], v129 offset:14336
	ds_read_b64_tr_b16 v[246:247], v129 offset:15360
	ds_read_b64_tr_b16 v[248:249], v130 offset:14336
	v_fmamk_f32 v48, v48, 0x3e38aa3b, v200
	v_fmamk_f32 v49, v49, 0x3e38aa3b, v201
	v_fmamk_f32 v50, v50, 0x3e38aa3b, v202
	v_fmamk_f32 v51, v51, 0x3e38aa3b, v203
	v_fmamk_f32 v52, v52, 0x3e38aa3b, v204
	v_fmamk_f32 v53, v53, 0x3e38aa3b, v205
	v_fmamk_f32 v54, v54, 0x3e38aa3b, v206
	v_fmamk_f32 v55, v55, 0x3e38aa3b, v207
	v_fmamk_f32 v56, v56, 0x3e38aa3b, v208
	v_fmamk_f32 v57, v57, 0x3e38aa3b, v209
	v_fmamk_f32 v58, v58, 0x3e38aa3b, v210
	v_fmamk_f32 v59, v59, 0x3e38aa3b, v211
	v_fmamk_f32 v60, v60, 0x3e38aa3b, v252
	v_fmamk_f32 v61, v61, 0x3e38aa3b, v253
	v_fmamk_f32 v62, v62, 0x3e38aa3b, v254
	v_fmamk_f32 v63, v63, 0x3e38aa3b, v255
	v_max3_f32 v125, v32, v33, v34
	v_max3_f32 v126, v35, v36, v37
	v_max3_f32 v127, v38, v39, v40
	v_max3_f32 v128, v41, v42, v43
	v_max3_f32 v125, v125, v44, v45
	v_max3_f32 v126, v126, v46, v47
	v_max3_f32 v127, v127, v48, v49
	v_max3_f32 v128, v128, v50, v51
	v_max3_f32 v125, v125, v52, v53
	v_max3_f32 v126, v126, v54, v55
	v_max3_f32 v127, v127, v56, v57
	v_max3_f32 v128, v128, v58, v59
	v_max3_f32 v125, v125, v60, v61
	v_max3_f32 v126, v126, v62, v63
	v_max3_f32 v125, v125, v126, v127
	v_max_f32_e32 v125, v125, v128
	v_mov_b32_e32 v126, v125
	v_mov_b32_e32 v127, v125
	s_nop 1
	v_permlane32_swap_b32_e32 v126, v127
	v_max_f32_e32 v125, v126, v127
	v_add_f32_e32 v126, 0x41000000, v165
	v_cmp_gt_f32_e32 vcc, v125, v126
	s_cbranch_vccz .Lb_pv
	v_add_f32_e32 v125, v125, v164
	v_max_f32_e32 v127, v119, v125
	v_sub_f32_e32 v126, v119, v127
	v_exp_f32_e32 v126, v126
	v_sub_f32_e32 v128, v164, v127
	v_mov_b32_e32 v119, v127
	v_add_f32_e32 v32, v32, v128
	v_add_f32_e32 v33, v33, v128
	v_add_f32_e32 v34, v34, v128
	v_add_f32_e32 v35, v35, v128
	v_add_f32_e32 v36, v36, v128
	v_add_f32_e32 v37, v37, v128
	v_add_f32_e32 v38, v38, v128
	v_add_f32_e32 v39, v39, v128
	v_add_f32_e32 v40, v40, v128
	v_add_f32_e32 v41, v41, v128
	v_add_f32_e32 v42, v42, v128
	v_add_f32_e32 v43, v43, v128
	v_add_f32_e32 v44, v44, v128
	v_add_f32_e32 v45, v45, v128
	v_add_f32_e32 v46, v46, v128
	v_add_f32_e32 v47, v47, v128
	v_add_f32_e32 v48, v48, v128
	v_add_f32_e32 v49, v49, v128
	v_add_f32_e32 v50, v50, v128
	v_add_f32_e32 v51, v51, v128
	v_add_f32_e32 v52, v52, v128
	v_add_f32_e32 v53, v53, v128
	v_add_f32_e32 v54, v54, v128
	v_add_f32_e32 v55, v55, v128
	v_add_f32_e32 v56, v56, v128
	v_add_f32_e32 v57, v57, v128
	v_add_f32_e32 v58, v58, v128
	v_add_f32_e32 v59, v59, v128
	v_add_f32_e32 v60, v60, v128
	v_add_f32_e32 v61, v61, v128
	v_add_f32_e32 v62, v62, v128
	v_add_f32_e32 v63, v63, v128
	v_pk_mul_f32 v[0:1], v[0:1], v[126:127] op_sel_hi:[1,0]
	v_pk_mul_f32 v[2:3], v[2:3], v[126:127] op_sel_hi:[1,0]
	v_pk_mul_f32 v[4:5], v[4:5], v[126:127] op_sel_hi:[1,0]
	v_pk_mul_f32 v[6:7], v[6:7], v[126:127] op_sel_hi:[1,0]
	v_pk_mul_f32 v[8:9], v[8:9], v[126:127] op_sel_hi:[1,0]
	v_pk_mul_f32 v[10:11], v[10:11], v[126:127] op_sel_hi:[1,0]
	v_pk_mul_f32 v[12:13], v[12:13], v[126:127] op_sel_hi:[1,0]
	v_pk_mul_f32 v[14:15], v[14:15], v[126:127] op_sel_hi:[1,0]
	v_pk_mul_f32 v[16:17], v[16:17], v[126:127] op_sel_hi:[1,0]
	v_pk_mul_f32 v[18:19], v[18:19], v[126:127] op_sel_hi:[1,0]
	v_pk_mul_f32 v[20:21], v[20:21], v[126:127] op_sel_hi:[1,0]
	v_pk_mul_f32 v[22:23], v[22:23], v[126:127] op_sel_hi:[1,0]
	v_pk_mul_f32 v[24:25], v[24:25], v[126:127] op_sel_hi:[1,0]
	v_pk_mul_f32 v[26:27], v[26:27], v[126:127] op_sel_hi:[1,0]
	v_pk_mul_f32 v[28:29], v[28:29], v[126:127] op_sel_hi:[1,0]
	v_pk_mul_f32 v[30:31], v[30:31], v[126:127] op_sel_hi:[1,0]
	v_mul_f32_e32 v101, v101, v126
	v_mul_f32_e32 v128, 0xc0b17218, v127
	v_mov_b32_e32 v136, v128
	v_mov_b32_e32 v137, v128
	v_mov_b32_e32 v138, v128
	v_mov_b32_e32 v139, v128
	v_mov_b32_e32 v140, v128
	v_mov_b32_e32 v141, v128
	v_mov_b32_e32 v142, v128
	v_mov_b32_e32 v143, v128
	v_mov_b32_e32 v144, v128
	v_mov_b32_e32 v145, v128
	v_mov_b32_e32 v146, v128
	v_mov_b32_e32 v147, v128
	v_mov_b32_e32 v148, v128
	v_mov_b32_e32 v149, v128
	v_mov_b32_e32 v150, v128
	v_mov_b32_e32 v151, v128
	v_mov_b32_e32 v164, v127
	v_mov_b32_e32 v165, 0
.Lb_pv:
	v_exp_f32_e32 v32, v32
	v_exp_f32_e32 v33, v33
	v_exp_f32_e32 v34, v34
	v_exp_f32_e32 v35, v35
	v_exp_f32_e32 v36, v36
	v_exp_f32_e32 v37, v37
	v_exp_f32_e32 v38, v38
	v_exp_f32_e32 v39, v39
	v_add_f32_e32 v125, v32, v33
	v_add_f32_e32 v126, v34, v35
	v_cvt_pk_bf16_f32 v32, v32, v33
	v_cvt_pk_bf16_f32 v33, v34, v35
	v_cvt_pk_bf16_f32 v34, v36, v37
	v_cvt_pk_bf16_f32 v35, v38, v39
	v_add_f32_e32 v127, v36, v37
	v_add_f32_e32 v125, v125, v38
	v_add_f32_e32 v126, v126, v39
	s_waitcnt lgkmcnt(4)
	v_mfma_f32_32x32x16_bf16 v[16:31], v[152:155], v[32:35], v[16:31]
	ds_read_b64_tr_b16 v[250:251], v130 offset:15360
	v_exp_f32_e32 v40, v40
	v_exp_f32_e32 v41, v41
	v_exp_f32_e32 v42, v42
	v_exp_f32_e32 v43, v43
	s_waitcnt lgkmcnt(5)
	v_mfma_f32_32x32x16_bf16 v[0:15], v[156:159], v[32:35], v[0:15]
	v_exp_f32_e32 v44, v44
	v_exp_f32_e32 v45, v45
	v_exp_f32_e32 v46, v46
	v_exp_f32_e32 v47, v47
	v_add_f32_e32 v125, v125, v40
	v_add_f32_e32 v126, v126, v41
	v_add_f32_e32 v127, v127, v42
	v_add_f32_e32 v125, v125, v43
	v_cvt_pk_bf16_f32 v40, v40, v41
	v_cvt_pk_bf16_f32 v41, v42, v43
	v_cvt_pk_bf16_f32 v42, v44, v45
	v_cvt_pk_bf16_f32 v43, v46, v47
	v_add_f32_e32 v126, v126, v44
	v_add_f32_e32 v127, v127, v45
	v_add_f32_e32 v125, v125, v46
	v_add_f32_e32 v126, v126, v47
	s_waitcnt lgkmcnt(5)
	v_mfma_f32_32x32x16_bf16 v[16:31], v[160:163], v[40:43], v[16:31]
	v_exp_f32_e32 v48, v48
	v_exp_f32_e32 v49, v49
	v_exp_f32_e32 v50, v50
	v_exp_f32_e32 v51, v51
	s_waitcnt lgkmcnt(5)
	v_mfma_f32_32x32x16_bf16 v[0:15], v[184:187], v[40:43], v[0:15]
	v_exp_f32_e32 v52, v52
	v_exp_f32_e32 v53, v53
	v_exp_f32_e32 v54, v54
	v_exp_f32_e32 v55, v55
	v_add_f32_e32 v125, v125, v48
	v_add_f32_e32 v126, v126, v49
	v_add_f32_e32 v127, v127, v50
	v_add_f32_e32 v125, v125, v51
	v_cvt_pk_bf16_f32 v48, v48, v49
	v_cvt_pk_bf16_f32 v49, v50, v51
	v_cvt_pk_bf16_f32 v50, v52, v53
	v_cvt_pk_bf16_f32 v51, v54, v55
	v_add_f32_e32 v126, v126, v52
	v_add_f32_e32 v127, v127, v53
	v_add_f32_e32 v125, v125, v54
	v_add_f32_e32 v126, v126, v55
	s_waitcnt lgkmcnt(5)
	v_mfma_f32_32x32x16_bf16 v[16:31], v[188:191], v[48:51], v[16:31]
	v_exp_f32_e32 v56, v56
	v_exp_f32_e32 v57, v57
	v_exp_f32_e32 v58, v58
	v_exp_f32_e32 v59, v59
	s_waitcnt lgkmcnt(4)
	v_mfma_f32_32x32x16_bf16 v[0:15], v[192:195], v[48:51], v[0:15]
	v_exp_f32_e32 v60, v60
	v_exp_f32_e32 v61, v61
	v_exp_f32_e32 v62, v62
	v_exp_f32_e32 v63, v63
	v_add_f32_e32 v125, v125, v56
	v_add_f32_e32 v126, v126, v57
	v_add_f32_e32 v127, v127, v58
	v_add_f32_e32 v125, v125, v59
	v_cvt_pk_bf16_f32 v56, v56, v57
	v_cvt_pk_bf16_f32 v57, v58, v59
	v_cvt_pk_bf16_f32 v58, v60, v61
	v_cvt_pk_bf16_f32 v59, v62, v63
	v_add_f32_e32 v126, v126, v60
	v_add_f32_e32 v127, v127, v61
	v_add_f32_e32 v125, v125, v62
	v_add_f32_e32 v126, v126, v63
	s_waitcnt lgkmcnt(2)
	v_mfma_f32_32x32x16_bf16 v[16:31], v[244:247], v[56:59], v[16:31]
	s_waitcnt lgkmcnt(0)
	v_mfma_f32_32x32x16_bf16 v[0:15], v[248:251], v[56:59], v[0:15]
	v_add_f32_e32 v125, v125, v126
	v_add_f32_e32 v101, v101, v127
	v_add_f32_e32 v101, v101, v125
